# speedup vs baseline: 1.0190x; 1.0026x over previous
; #define SBAR() __builtin_amdgcn_sched_barrier(0)
; #define SLOAD(i, t) do { const long rb_ = TROW(t); const char* vt_ = (const char*)Vh + rb_ * (LDK * 2); const char* kt_ = (const char*)Kh + rb_ * (LDK * 2); \
;     sr_[i].vs0 = *(const bf16x8*)(vt_ + lo0); sr_[i].vs1 = *(const bf16x8*)(vt_ + lo0 + 32 * LDK * 2); \
;     sr_[i].ks0 = *(const bf16x8*)(kt_ + lo0); sr_[i].ks1 = *(const bf16x8*)(kt_ + lo0 + 32 * LDK * 2); } while (0)
; __device__ __forceinline__ void finishSM(f32x16& p0, f32x16& p1, float alpha, float& l_reg, bf16x8& pa0, bf16x8& pa1, bf16x8& pa2, bf16x8& pa3) {
; #pragma unroll
;   for (int r = 0; r < 16; ++r) p1[r] = __builtin_amdgcn_exp2f(p1[r]);
;   float ps = 0;
; #pragma unroll
;   for (int r = 0; r < 16; ++r) ps += p0[r];
; #pragma unroll
;   for (int r = 0; r < 16; ++r) ps += p1[r];
;   { auto rr = __builtin_amdgcn_permlane32_swap(__float_as_uint(ps), __float_as_uint(ps), false, false);
;     ps = __uint_as_float(rr[0]) + __uint_as_float(rr[1]); }
;   l_reg = l_reg * alpha + ps;
;     ...
;   PK4(p0, 0, pa0); PK4(p0, 8, pa1); PK4(p1, 0, pa2); PK4(p1, 8, pa3);
; template <bool META>
; __device__ __forceinline__ void attn_unit(const bf16_t* Q, bf16_t* Oo, const bf16_t* __restrict__ Kb, const bf16_t* __restrict__ Vb, int b, int kvh, int h, int qb, char* lds, const int tid, const float* qn, const float* RT) {
;     ...
;   for (int j = 1; j + 1 < NT; j += 2) {
;     const int bn = bc == 2 ? 0 : bc + 1, bp = bc == 0 ? 2 : bc - 1;
;     SBAR(); qkt(pB0, pB1, (bf16_t*)((char*)K_lds + bc * SHM_K), qr, r32, hi);
;     finishSM(pA0, pA1, alA, l_reg, pa0, pa1, pa2, pa3); SBAR();
;     SLOAD(SO, j + 1);
.LBB0_260:
	s_mov_b32 s6, s28
	v_sub_co_u32_e64 v66, s[0:1], s6, 1
	s_and_b64 s[0:1], s[0:1], exec
	v_readfirstlane_b32 s0, v66
	s_cselect_b32 s28, 2, s0
	s_lshl_b32 s9, s6, 14
	s_add_i32 s0, s9, 0
	v_add_u32_e32 v195, s0, v182
	ds_read_b128 v[66:69], v195 offset:49152
	ds_read_b128 v[70:73], v195 offset:50176
	ds_read_b128 v[210:213], v195 offset:51200
	ds_read_b128 v[214:217], v195 offset:52224
	s_waitcnt lgkmcnt(3)
	v_mfma_f32_32x32x16_bf16 v[82:97], v[66:69], v[98:101], 0
	v_exp_f32_e32 v144, v144
	v_exp_f32_e32 v145, v145
	v_exp_f32_e32 v142, v142
	v_exp_f32_e32 v143, v143
	v_exp_f32_e32 v140, v140
	v_exp_f32_e32 v141, v141
	v_exp_f32_e32 v138, v138
	s_waitcnt lgkmcnt(2)
	v_mfma_f32_32x32x16_bf16 v[66:81], v[70:73], v[98:101], 0
	v_exp_f32_e32 v139, v139
	v_exp_f32_e32 v136, v136
	v_exp_f32_e32 v137, v137
	v_exp_f32_e32 v134, v134
	v_exp_f32_e32 v135, v135
	v_exp_f32_e32 v132, v132
	v_exp_f32_e32 v133, v133
	s_waitcnt lgkmcnt(1)
	v_mfma_f32_32x32x16_bf16 v[82:97], v[210:213], v[102:105], v[82:97]
	v_exp_f32_e32 v130, v130
	v_exp_f32_e32 v131, v131
	s_waitcnt lgkmcnt(0)
	v_mfma_f32_32x32x16_bf16 v[66:81], v[214:217], v[102:105], v[66:81]
	ds_read_b128 v[210:213], v195 offset:53248
	ds_read_b128 v[214:217], v195 offset:54272
	s_waitcnt lgkmcnt(1)
	v_mfma_f32_32x32x16_bf16 v[82:97], v[210:213], v[106:109], v[82:97]
	s_waitcnt lgkmcnt(0)
	v_mfma_f32_32x32x16_bf16 v[66:81], v[214:217], v[106:109], v[66:81]
	ds_read_b128 v[210:213], v195 offset:55296
	ds_read_b128 v[214:217], v195 offset:56320
	s_waitcnt lgkmcnt(1)
	v_mfma_f32_32x32x16_bf16 v[82:97], v[210:213], v[110:113], v[82:97]
	s_waitcnt lgkmcnt(0)
	v_mfma_f32_32x32x16_bf16 v[66:81], v[214:217], v[110:113], v[66:81]
	ds_read_b128 v[210:213], v195 offset:57344
	ds_read_b128 v[214:217], v195 offset:58368
	s_waitcnt lgkmcnt(1)
	v_mfma_f32_32x32x16_bf16 v[82:97], v[210:213], v[114:117], v[82:97]
	s_waitcnt lgkmcnt(0)
	v_mfma_f32_32x32x16_bf16 v[66:81], v[214:217], v[114:117], v[66:81]
	ds_read_b128 v[210:213], v195 offset:59392
	ds_read_b128 v[214:217], v195 offset:60416
	s_waitcnt lgkmcnt(1)
	v_mfma_f32_32x32x16_bf16 v[82:97], v[210:213], v[118:121], v[82:97]
	s_waitcnt lgkmcnt(0)
	v_mfma_f32_32x32x16_bf16 v[66:81], v[214:217], v[118:121], v[66:81]
	ds_read_b128 v[210:213], v195 offset:61440
	ds_read_b128 v[214:217], v195 offset:62464
	s_waitcnt lgkmcnt(1)
	v_mfma_f32_32x32x16_bf16 v[82:97], v[210:213], v[122:125], v[82:97]
	s_waitcnt lgkmcnt(0)
	v_mfma_f32_32x32x16_bf16 v[66:81], v[214:217], v[122:125], v[66:81]
	ds_read_b128 v[210:213], v195 offset:63488
	ds_read_b128 v[214:217], v195 offset:64512
	v_add_f32_e32 v193, v147, v146
	v_add_f32_e32 v193, v148, v193
	v_add_f32_e32 v193, v159, v193
	v_add_f32_e32 v193, v160, v193
	v_add_f32_e32 v193, v209, v193
	v_add_f32_e32 v193, v149, v193
	v_add_f32_e32 v193, v161, v193
	v_add_f32_e32 v193, v151, v193
	v_add_f32_e32 v193, v153, v193
	v_add_f32_e32 v193, v154, v193
	v_add_f32_e32 v193, v157, v193
	v_add_f32_e32 v193, v152, v193
	v_add_f32_e32 v193, v155, v193
	v_add_f32_e32 v193, v156, v193
	v_add_f32_e32 v193, v158, v193
	v_add_f32_e32 v193, v144, v193
	v_add_f32_e32 v193, v145, v193
	v_add_f32_e32 v193, v142, v193
	v_add_f32_e32 v193, v143, v193
	v_add_f32_e32 v193, v140, v193
	v_add_f32_e32 v193, v141, v193
	v_add_f32_e32 v193, v138, v193
	v_add_f32_e32 v193, v139, v193
	v_add_f32_e32 v193, v136, v193
	v_add_f32_e32 v193, v137, v193
	s_waitcnt lgkmcnt(1)
	v_mfma_f32_32x32x16_bf16 v[82:97], v[210:213], v[126:129], v[82:97]
	v_add_f32_e32 v193, v134, v193
	v_add_f32_e32 v193, v135, v193
	v_add_f32_e32 v193, v132, v193
	v_add_f32_e32 v193, v133, v193
	v_add_f32_e32 v193, v130, v193
	v_add_f32_e32 v193, v131, v193
	v_mov_b32_e32 v195, v193
	s_waitcnt lgkmcnt(0)
	v_mfma_f32_32x32x16_bf16 v[66:81], v[214:217], v[126:129], v[66:81]
	v_cvt_pk_bf16_f32 v146, v146, v147
	v_cvt_pk_bf16_f32 v147, v148, v159
	v_cvt_pk_bf16_f32 v148, v160, v209
	v_permlane32_swap_b32_e32 v193, v195
	v_cvt_pk_bf16_f32 v149, v149, v161
	v_permlane32_swap_b32_e32 v146, v148
	v_cvt_pk_bf16_f32 v210, v151, v153
	v_cvt_pk_bf16_f32 v211, v154, v157
	v_cvt_pk_bf16_f32 v212, v152, v155
	v_cvt_pk_bf16_f32 v213, v156, v158
	v_cvt_pk_bf16_f32 v152, v144, v145
	v_cvt_pk_bf16_f32 v153, v142, v143
	v_cvt_pk_bf16_f32 v154, v140, v141
	v_cvt_pk_bf16_f32 v155, v138, v139
	v_cvt_pk_bf16_f32 v156, v136, v137
	v_cvt_pk_bf16_f32 v157, v134, v135
	v_cvt_pk_bf16_f32 v158, v132, v133
	v_cvt_pk_bf16_f32 v159, v130, v131
	v_permlane32_swap_b32_e32 v147, v149
	v_permlane32_swap_b32_e32 v210, v212
	v_permlane32_swap_b32_e32 v211, v213
	v_permlane32_swap_b32_e32 v152, v154
	v_permlane32_swap_b32_e32 v153, v155
	v_permlane32_swap_b32_e32 v156, v158
	v_permlane32_swap_b32_e32 v157, v159
	s_lshl_b32 s8, s28, 14
	v_add_u32_e32 v151, s8, v178
	ds_read_b64_tr_b16 v[214:215], v151 offset:0
	ds_read_b64_tr_b16 v[216:217], v151 offset:0x800
	ds_read_b64_tr_b16 v[218:219], v151 offset:0x1000
	ds_read_b64_tr_b16 v[220:221], v151 offset:0x1800
	ds_read_b64_tr_b16 v[222:223], v151 offset:0x2000
	ds_read_b64_tr_b16 v[224:225], v151 offset:0x2800
	ds_read_b64_tr_b16 v[226:227], v151 offset:0x3000
	ds_read_b64_tr_b16 v[228:229], v151 offset:0x3800
	s_cmpk_lg_i32 s4, 0xfd
	s_cselect_b64 s[0:1], -1, 0
	s_cmpk_eq_i32 s4, 0xfd
	s_cselect_b64 s[40:41], -1, 0
	s_and_b64 s[10:11], s[40:41], exec
	s_cselect_b32 s11, s44, s91
	s_cselect_b32 s10, s31, s90
	s_lshl_b64 s[10:11], s[10:11], 9
	s_add_i32 s19, s9, 0x4000
	s_cmp_lg_u32 s6, 2
	s_cselect_b32 s19, s19, 0
	s_add_i32 s19, s19, s18
	s_add_u32 s16, s12, s10
	s_addc_u32 s17, s13, s11
	s_mov_b32 m0, s19
	s_nop 0
	global_load_lds_dwordx4 v187, s[16:17]
	s_add_i32 m0, s19, 0x380
	s_nop 0
	global_load_lds_dwordx4 v187, s[16:17] offset:128
	s_add_u32 s16, s14, s10
	s_addc_u32 s17, s15, s11
	s_add_i32 m0, s19, 0xc000
	s_nop 0
	global_load_lds_dwordx4 v188, s[16:17]
	s_add_u32 s16, s16, 0x4000
	s_addc_u32 s17, s17, 0
	s_add_i32 m0, s19, 0xc400
	s_nop 0
	global_load_lds_dwordx4 v188, s[16:17]
	s_waitcnt lgkmcnt(6)
; #define SBAR() __builtin_amdgcn_sched_barrier(0)
; __device__ __forceinline__ void partialSM(f32x16& p0, f32x16& p1, float& m_reg, float& mn, float& alpha) {
;   constexpr float C = ASCALE * 1.4426950408889634f;
;   float pmax = p0[0];
; #pragma unroll
;   for (int r = 1; r < 16; ++r) pmax = fmaxf(pmax, p0[r]);
; #pragma unroll
;   for (int r = 0; r < 16; ++r) pmax = fmaxf(pmax, p1[r]);
;   { auto rr = __builtin_amdgcn_permlane32_swap(__float_as_uint(pmax), __float_as_uint(pmax), false, false);
;     pmax = fmaxf(__uint_as_float(rr[0]), __uint_as_float(rr[1])); }
;   if (__builtin_expect(__all(pmax - m_reg <= ATHR / ASCALE), 1)) { mn = m_reg; alpha = 1.f; }
;   else { mn = fmaxf(m_reg, pmax); alpha = __builtin_amdgcn_exp2f((m_reg - mn) * C); m_reg = mn; }
; template <int D0> __device__ __forceinline__ void pv_one(f32x16& od, int vb, bf16x8 pa0, bf16x8 pa1, bf16x8 pa2, bf16x8 pa3) {
;   const s16x4 l0 = tr_read<v_rd_off(D0, 0, 0)>(vb), h0 = tr_read<v_rd_off(D0, 0, 1)>(vb), l1 = tr_read<v_rd_off(D0, 1, 0)>(vb), h1 = tr_read<v_rd_off(D0, 1, 1)>(vb);
;   const s16x4 l2 = tr_read<v_rd_off(D0, 2, 0)>(vb), h2 = tr_read<v_rd_off(D0, 2, 1)>(vb), l3 = tr_read<v_rd_off(D0, 3, 0)>(vb), h3 = tr_read<v_rd_off(D0, 3, 1)>(vb);
;   asm volatile("s_waitcnt lgkmcnt(0)" ::: "memory"); SBAR();
;     ...
;   od = __builtin_amdgcn_mfma_f32_32x32x16_bf16(pa0, PK(l0, h0), od, 0, 0, 0);
;   od = __builtin_amdgcn_mfma_f32_32x32x16_bf16(pa1, PK(l1, h1), od, 0, 0, 0);
;   od = __builtin_amdgcn_mfma_f32_32x32x16_bf16(pa2, PK(l2, h2), od, 0, 0, 0);
;   od = __builtin_amdgcn_mfma_f32_32x32x16_bf16(pa3, PK(l3, h3), od, 0, 0, 0);
;     ...
; }
; __device__ __forceinline__ void pv_d0(f32x16* o, int vb, bf16x8 pa0, bf16x8 pa1, bf16x8 pa2, bf16x8 pa3) {
;   pv_one<0>(o[0], vb, pa0, pa1, pa2, pa3); pv_one<1>(o[1], vb, pa0, pa1, pa2, pa3); pv_one<2>(o[2], vb, pa0, pa1, pa2, pa3); pv_one<3>(o[3], vb, pa0, pa1, pa2, pa3);
	s_nop 0
	v_mfma_f32_32x32x16_bf16 v[2:17], v[146:149], v[214:217], v[2:17]
	ds_read_b64_tr_b16 v[214:215], v151 offset:0x200
	ds_read_b64_tr_b16 v[216:217], v151 offset:0xa00
	s_waitcnt lgkmcnt(6)
	v_mfma_f32_32x32x16_bf16 v[2:17], v[210:213], v[218:221], v[2:17]
	ds_read_b64_tr_b16 v[218:219], v151 offset:0x1200
	ds_read_b64_tr_b16 v[220:221], v151 offset:0x1a00
	s_waitcnt lgkmcnt(6)
	v_mfma_f32_32x32x16_bf16 v[2:17], v[152:155], v[222:225], v[2:17]
	ds_read_b64_tr_b16 v[222:223], v151 offset:0x2200
	ds_read_b64_tr_b16 v[224:225], v151 offset:0x2a00
	s_waitcnt lgkmcnt(6)
	v_mfma_f32_32x32x16_bf16 v[2:17], v[156:159], v[226:229], v[2:17]
	ds_read_b64_tr_b16 v[226:227], v151 offset:0x3200
	ds_read_b64_tr_b16 v[228:229], v151 offset:0x3a00
	s_waitcnt lgkmcnt(6)
	v_mfma_f32_32x32x16_bf16 v[50:65], v[146:149], v[214:217], v[50:65]
	ds_read_b64_tr_b16 v[214:215], v151 offset:0x400
	ds_read_b64_tr_b16 v[216:217], v151 offset:0xc00
	s_waitcnt lgkmcnt(6)
	v_mfma_f32_32x32x16_bf16 v[50:65], v[210:213], v[218:221], v[50:65]
	ds_read_b64_tr_b16 v[218:219], v151 offset:0x1400
	ds_read_b64_tr_b16 v[220:221], v151 offset:0x1c00
	s_waitcnt lgkmcnt(6)
	v_mfma_f32_32x32x16_bf16 v[50:65], v[152:155], v[222:225], v[50:65]
	ds_read_b64_tr_b16 v[222:223], v151 offset:0x2400
	ds_read_b64_tr_b16 v[224:225], v151 offset:0x2c00
	s_waitcnt lgkmcnt(6)
	v_mfma_f32_32x32x16_bf16 v[50:65], v[156:159], v[226:229], v[50:65]
	ds_read_b64_tr_b16 v[226:227], v151 offset:0x3400
	ds_read_b64_tr_b16 v[228:229], v151 offset:0x3c00
	s_waitcnt lgkmcnt(6)
	v_mfma_f32_32x32x16_bf16 v[34:49], v[146:149], v[214:217], v[34:49]
	ds_read_b64_tr_b16 v[214:215], v151 offset:0x600
	ds_read_b64_tr_b16 v[216:217], v151 offset:0xe00
	s_waitcnt lgkmcnt(6)
	v_mfma_f32_32x32x16_bf16 v[34:49], v[210:213], v[218:221], v[34:49]
	ds_read_b64_tr_b16 v[218:219], v151 offset:0x1600
	ds_read_b64_tr_b16 v[220:221], v151 offset:0x1e00
	s_waitcnt lgkmcnt(6)
	v_mfma_f32_32x32x16_bf16 v[34:49], v[152:155], v[222:225], v[34:49]
	ds_read_b64_tr_b16 v[222:223], v151 offset:0x2600
	ds_read_b64_tr_b16 v[224:225], v151 offset:0x2e00
	s_waitcnt lgkmcnt(6)
	v_mfma_f32_32x32x16_bf16 v[34:49], v[156:159], v[226:229], v[34:49]
	ds_read_b64_tr_b16 v[226:227], v151 offset:0x3600
	ds_read_b64_tr_b16 v[228:229], v151 offset:0x3e00
	s_waitcnt lgkmcnt(6)
	v_mfma_f32_32x32x16_bf16 v[18:33], v[146:149], v[214:217], v[18:33]
	v_max_f32_e32 v146, v82, v83
	v_max3_f32 v146, v146, v84, v85
	v_max3_f32 v146, v146, v86, v87
	v_max3_f32 v146, v146, v88, v89
	v_max3_f32 v146, v146, v90, v91
	v_max3_f32 v146, v146, v92, v93
	v_max3_f32 v146, v146, v94, v95
	v_max3_f32 v146, v146, v96, v97
	v_max3_f32 v146, v146, v66, v67
	s_waitcnt lgkmcnt(4)
	v_mfma_f32_32x32x16_bf16 v[18:33], v[210:213], v[218:221], v[18:33]
	v_max3_f32 v146, v146, v68, v69
	v_max3_f32 v146, v146, v70, v71
	v_max3_f32 v146, v146, v72, v73
	v_max3_f32 v146, v146, v74, v75
	v_max3_f32 v146, v146, v76, v77
	v_max3_f32 v146, v146, v78, v79
	v_max3_f32 v146, v146, v80, v81
	v_mov_b32_e32 v147, v146
	s_waitcnt lgkmcnt(2)
	v_mfma_f32_32x32x16_bf16 v[18:33], v[152:155], v[222:225], v[18:33]
	s_nop 0
	v_permlane32_swap_b32_e32 v146, v147
	v_max_f32_e32 v146, v146, v147
	v_sub_f32_e32 v147, v146, v150
	v_cmp_ge_f32_e32 vcc, s25, v147
	v_max_f32_e32 v146, v150, v146
	v_sub_f32_e32 v147, v150, v146
	s_cmp_eq_u64 vcc, exec
	v_mul_f32_e32 v147, 0x3e0293ee, v147
	s_waitcnt lgkmcnt(0)
	v_mfma_f32_32x32x16_bf16 v[18:33], v[156:159], v[226:229], v[18:33]
	s_cselect_b64 s[42:43], -1, 0
	v_exp_f32_e32 v147, v147
	s_add_i32 s7, s9, 0x4000
	s_cmp_lg_u32 s6, 2
	s_cselect_b32 s6, s7, 0
	s_add_i32 s10, s6, 0
	v_cndmask_b32_e64 v196, v147, 1.0, s[42:43]
	v_cmp_gt_f32_e32 vcc, 1.0, v196
	s_cbranch_vccz .LBB0_264
	s_and_saveexec_b64 s[6:7], s[38:39]
	ds_write_b32 v190, v196 offset:128
	s_or_b64 exec, exec, s[6:7]
	s_waitcnt lgkmcnt(0)
	v_add_u32_e32 v147, v173, v181
	ds_read_b128 v[152:155], v147 offset:224
	ds_read_b128 v[156:159], v147 offset:192
	ds_read_b128 v[210:213], v147 offset:160
	ds_read_b128 v[214:217], v147 offset:128
	s_waitcnt lgkmcnt(3)
	v_pk_mul_f32 v[14:15], v[14:15], v[152:153]
	s_waitcnt lgkmcnt(2)
	v_pk_mul_f32 v[10:11], v[10:11], v[156:157]
	s_waitcnt lgkmcnt(1)
	v_pk_mul_f32 v[6:7], v[6:7], v[210:211]
	v_pk_mul_f32 v[16:17], v[16:17], v[154:155]
	v_pk_mul_f32 v[12:13], v[12:13], v[158:159]
	v_pk_mul_f32 v[8:9], v[8:9], v[212:213]
	s_waitcnt lgkmcnt(0)
	v_pk_mul_f32 v[4:5], v[4:5], v[216:217]
	v_pk_mul_f32 v[2:3], v[2:3], v[214:215]
	v_pk_mul_f32 v[62:63], v[62:63], v[152:153]
	v_pk_mul_f32 v[58:59], v[58:59], v[156:157]
	v_pk_mul_f32 v[54:55], v[54:55], v[210:211]
	v_pk_mul_f32 v[64:65], v[64:65], v[154:155]
	v_pk_mul_f32 v[60:61], v[60:61], v[158:159]
	v_pk_mul_f32 v[56:57], v[56:57], v[212:213]
	v_pk_mul_f32 v[52:53], v[52:53], v[216:217]
	v_pk_mul_f32 v[50:51], v[50:51], v[214:215]
	v_pk_mul_f32 v[46:47], v[46:47], v[152:153]
	v_pk_mul_f32 v[42:43], v[42:43], v[156:157]
	v_pk_mul_f32 v[38:39], v[38:39], v[210:211]
	v_pk_mul_f32 v[48:49], v[48:49], v[154:155]
	v_pk_mul_f32 v[44:45], v[44:45], v[158:159]
	v_pk_mul_f32 v[40:41], v[40:41], v[212:213]
	v_pk_mul_f32 v[36:37], v[36:37], v[216:217]
	v_pk_mul_f32 v[34:35], v[34:35], v[214:215]
	v_pk_mul_f32 v[30:31], v[30:31], v[152:153]
	v_pk_mul_f32 v[26:27], v[26:27], v[156:157]
	v_pk_mul_f32 v[22:23], v[22:23], v[210:211]
	v_pk_mul_f32 v[32:33], v[32:33], v[154:155]
	v_pk_mul_f32 v[28:29], v[28:29], v[158:159]
	v_pk_mul_f32 v[24:25], v[24:25], v[212:213]
	v_pk_mul_f32 v[20:21], v[20:21], v[216:217]
	v_pk_mul_f32 v[18:19], v[18:19], v[214:215]
; #define SBAR() __builtin_amdgcn_sched_barrier(0)
; __device__ __forceinline__ void finishSM(f32x16& p0, f32x16& p1, float alpha, float& l_reg, bf16x8& pa0, bf16x8& pa1, bf16x8& pa2, bf16x8& pa3) {
; #pragma unroll
;   for (int r = 0; r < 16; ++r) p1[r] = __builtin_amdgcn_exp2f(p1[r]);
;   float ps = 0;
; #pragma unroll
;   for (int r = 0; r < 16; ++r) ps += p0[r];
; #pragma unroll
;   for (int r = 0; r < 16; ++r) ps += p1[r];
;   { auto rr = __builtin_amdgcn_permlane32_swap(__float_as_uint(ps), __float_as_uint(ps), false, false);
;     ps = __uint_as_float(rr[0]) + __uint_as_float(rr[1]); }
;   l_reg = l_reg * alpha + ps;
;     ...
;   PK4(p0, 0, pa0); PK4(p0, 8, pa1); PK4(p1, 0, pa2); PK4(p1, 8, pa3);
; __device__ __forceinline__ void mask_last(f32x16& p0, f32x16& p1) {
; #pragma unroll
;   for (int r = 8; r < 16; ++r) p0[r] = -1e30f;
; #pragma unroll
;   for (int r = 0; r < 16; ++r) p1[r] = -1e30f;
; }
; template <bool META>
; __device__ __forceinline__ void attn_unit(const bf16_t* Q, bf16_t* Oo, const bf16_t* __restrict__ Kb, const bf16_t* __restrict__ Vb, int b, int kvh, int h, int qb, char* lds, const int tid, const float* qn, const float* RT) {
;     ...
;     SBAR(); qkt(pA0, pA1, (bf16_t*)((char*)K_lds + bn * SHM_K), qr, r32, hi);
;     if (j + 1 == NT - 1) mask_last(pA0, pA1);
;     finishSM(pB0, pB1, alB, l_reg, pa0, pa1, pa2, pa3); SBAR();
.LBB0_264:
	v_cndmask_b32_e64 v209, v146, v150, s[42:43]
	v_mul_f32_e32 v154, 0xbe0293ee, v209
	s_add_i32 s4, s4, 2
	v_fmamk_f32 v82, v82, 0x3e0293ee, v154
	v_fmamk_f32 v83, v83, 0x3e0293ee, v154
	v_fmamk_f32 v84, v84, 0x3e0293ee, v154
	v_fmamk_f32 v85, v85, 0x3e0293ee, v154
	v_fmamk_f32 v86, v86, 0x3e0293ee, v154
	v_fmamk_f32 v87, v87, 0x3e0293ee, v154
	v_fmamk_f32 v88, v88, 0x3e0293ee, v154
	v_fmamk_f32 v89, v89, 0x3e0293ee, v154
	v_fmamk_f32 v90, v90, 0x3e0293ee, v154
	v_fmamk_f32 v91, v91, 0x3e0293ee, v154
	v_fmamk_f32 v92, v92, 0x3e0293ee, v154
	v_fmamk_f32 v93, v93, 0x3e0293ee, v154
	v_fmamk_f32 v94, v94, 0x3e0293ee, v154
	v_fmamk_f32 v95, v95, 0x3e0293ee, v154
	v_fmamk_f32 v96, v96, 0x3e0293ee, v154
	v_fmamk_f32 v97, v97, 0x3e0293ee, v154
	v_fmamk_f32 v155, v66, 0x3e0293ee, v154
	v_fmamk_f32 v156, v67, 0x3e0293ee, v154
	v_fmamk_f32 v157, v68, 0x3e0293ee, v154
	v_fmamk_f32 v158, v69, 0x3e0293ee, v154
	v_fmamk_f32 v159, v70, 0x3e0293ee, v154
	v_fmamk_f32 v160, v71, 0x3e0293ee, v154
	v_fmamk_f32 v161, v72, 0x3e0293ee, v154
	v_fmamk_f32 v198, v73, 0x3e0293ee, v154
	v_fmamk_f32 v199, v74, 0x3e0293ee, v154
	v_fmamk_f32 v200, v75, 0x3e0293ee, v154
	v_fmamk_f32 v201, v76, 0x3e0293ee, v154
	v_fmamk_f32 v202, v77, 0x3e0293ee, v154
	v_fmamk_f32 v203, v78, 0x3e0293ee, v154
	v_fmamk_f32 v204, v79, 0x3e0293ee, v154
	v_fmamk_f32 v205, v80, 0x3e0293ee, v154
	v_fmac_f32_e32 v154, 0x3e0293ee, v81
	v_exp_f32_e32 v206, v82
	v_exp_f32_e32 v207, v83
	v_exp_f32_e32 v212, v84
	v_exp_f32_e32 v213, v85
	v_exp_f32_e32 v214, v86
	v_exp_f32_e32 v215, v87
	v_exp_f32_e32 v216, v88
	v_exp_f32_e32 v217, v89
	v_exp_f32_e32 v218, v90
	v_exp_f32_e32 v219, v91
	v_exp_f32_e32 v220, v92
	v_exp_f32_e32 v221, v93
	v_exp_f32_e32 v222, v94
	v_exp_f32_e32 v223, v95
	v_exp_f32_e32 v224, v96
	v_exp_f32_e32 v225, v97
	s_waitcnt vmcnt(0)
	s_waitcnt lgkmcnt(0)
	s_barrier
	v_add_u32_e32 v211, s10, v182
	ds_read_b128 v[66:69], v211 offset:49152
	ds_read_b128 v[82:85], v211 offset:50176
	ds_read_b128 v[146:149], v211 offset:51200
	ds_read_b128 v[150:153], v211 offset:52224
	v_exp_f32_e32 v155, v155
	s_waitcnt lgkmcnt(3)
	v_mfma_f32_32x32x16_bf16 v[66:81], v[66:69], v[98:101], 0
	v_exp_f32_e32 v156, v156
	v_exp_f32_e32 v157, v157
	v_exp_f32_e32 v158, v158
	v_exp_f32_e32 v159, v159
	v_exp_f32_e32 v160, v160
	v_exp_f32_e32 v161, v161
	v_exp_f32_e32 v198, v198
	s_waitcnt lgkmcnt(2)
	v_mfma_f32_32x32x16_bf16 v[82:97], v[82:85], v[98:101], 0
	v_exp_f32_e32 v199, v199
	v_exp_f32_e32 v200, v200
	v_exp_f32_e32 v201, v201
	v_exp_f32_e32 v202, v202
	v_exp_f32_e32 v203, v203
	v_exp_f32_e32 v204, v204
	v_exp_f32_e32 v205, v205
	s_waitcnt lgkmcnt(1)
	v_mfma_f32_32x32x16_bf16 v[66:81], v[146:149], v[102:105], v[66:81]
	v_exp_f32_e32 v226, v154
	v_cvt_pk_bf16_f32 v154, v155, v156
	s_waitcnt lgkmcnt(0)
	v_mfma_f32_32x32x16_bf16 v[82:97], v[150:153], v[102:105], v[82:97]
	ds_read_b128 v[146:149], v211 offset:53248
	ds_read_b128 v[150:153], v211 offset:54272
	s_waitcnt lgkmcnt(1)
	v_mfma_f32_32x32x16_bf16 v[66:81], v[146:149], v[106:109], v[66:81]
	s_waitcnt lgkmcnt(0)
	v_mfma_f32_32x32x16_bf16 v[82:97], v[150:153], v[106:109], v[82:97]
	ds_read_b128 v[146:149], v211 offset:55296
	ds_read_b128 v[150:153], v211 offset:56320
	s_waitcnt lgkmcnt(1)
	v_mfma_f32_32x32x16_bf16 v[66:81], v[146:149], v[110:113], v[66:81]
	s_waitcnt lgkmcnt(0)
	v_mfma_f32_32x32x16_bf16 v[82:97], v[150:153], v[110:113], v[82:97]
	ds_read_b128 v[146:149], v211 offset:57344
	ds_read_b128 v[150:153], v211 offset:58368
	s_waitcnt lgkmcnt(1)
	v_mfma_f32_32x32x16_bf16 v[66:81], v[146:149], v[114:117], v[66:81]
	s_waitcnt lgkmcnt(0)
	v_mfma_f32_32x32x16_bf16 v[82:97], v[150:153], v[114:117], v[82:97]
	ds_read_b128 v[146:149], v211 offset:59392
	ds_read_b128 v[150:153], v211 offset:60416
	s_waitcnt lgkmcnt(1)
	v_mfma_f32_32x32x16_bf16 v[66:81], v[146:149], v[118:121], v[66:81]
	s_waitcnt lgkmcnt(0)
	v_mfma_f32_32x32x16_bf16 v[82:97], v[150:153], v[118:121], v[82:97]
	ds_read_b128 v[146:149], v211 offset:61440
	ds_read_b128 v[150:153], v211 offset:62464
	s_waitcnt lgkmcnt(1)
	v_mfma_f32_32x32x16_bf16 v[66:81], v[146:149], v[122:125], v[66:81]
	s_waitcnt lgkmcnt(0)
	v_mfma_f32_32x32x16_bf16 v[82:97], v[150:153], v[122:125], v[82:97]
	ds_read_b128 v[146:149], v211 offset:63488
	ds_read_b128 v[150:153], v211 offset:64512
	s_waitcnt lgkmcnt(1)
	v_mfma_f32_32x32x16_bf16 v[66:81], v[146:149], v[126:129], v[66:81]
	v_add_f32_e32 v146, v207, v206
	v_add_f32_e32 v146, v212, v146
	v_add_f32_e32 v146, v213, v146
	v_add_f32_e32 v146, v214, v146
	v_add_f32_e32 v146, v215, v146
	v_add_f32_e32 v146, v216, v146
	v_add_f32_e32 v146, v217, v146
	v_add_f32_e32 v146, v218, v146
	v_add_f32_e32 v146, v219, v146
	v_add_f32_e32 v146, v220, v146
	v_add_f32_e32 v146, v221, v146
	v_add_f32_e32 v146, v222, v146
	v_add_f32_e32 v146, v223, v146
	v_add_f32_e32 v146, v224, v146
	v_add_f32_e32 v146, v225, v146
	v_add_f32_e32 v146, v155, v146
	v_add_f32_e32 v146, v156, v146
	v_add_f32_e32 v146, v157, v146
	v_add_f32_e32 v146, v158, v146
	v_add_f32_e32 v146, v159, v146
	v_add_f32_e32 v146, v160, v146
	v_add_f32_e32 v146, v161, v146
	v_add_f32_e32 v146, v198, v146
	v_add_f32_e32 v146, v199, v146
	v_add_f32_e32 v146, v200, v146
	s_waitcnt lgkmcnt(0)
	v_mfma_f32_32x32x16_bf16 v[82:97], v[150:153], v[126:129], v[82:97]
	v_add_f32_e32 v146, v201, v146
	v_add_f32_e32 v146, v202, v146
	v_add_f32_e32 v146, v203, v146
	v_add_f32_e32 v146, v204, v146
	v_add_f32_e32 v146, v205, v146
	v_add_f32_e32 v210, v226, v146
	v_mov_b32_e32 v211, v210
	v_cvt_pk_bf16_f32 v146, v206, v207
	v_cvt_pk_bf16_f32 v147, v212, v213
	v_cvt_pk_bf16_f32 v148, v214, v215
	v_cvt_pk_bf16_f32 v149, v216, v217
	v_cvt_pk_bf16_f32 v150, v218, v219
	v_cvt_pk_bf16_f32 v151, v220, v221
	v_cvt_pk_bf16_f32 v152, v222, v223
	v_cvt_pk_bf16_f32 v153, v224, v225
	v_cvt_pk_bf16_f32 v155, v157, v158
	v_cvt_pk_bf16_f32 v156, v159, v160
	v_cvt_pk_bf16_f32 v157, v161, v198
	v_cvt_pk_bf16_f32 v158, v199, v200
	v_cvt_pk_bf16_f32 v159, v201, v202
	v_cvt_pk_bf16_f32 v160, v203, v204
	v_cvt_pk_bf16_f32 v161, v205, v226
	v_permlane32_swap_b32_e32 v210, v211
	v_permlane32_swap_b32_e32 v146, v148
	v_permlane32_swap_b32_e32 v147, v149
	v_permlane32_swap_b32_e32 v150, v152
	v_permlane32_swap_b32_e32 v151, v153
	v_permlane32_swap_b32_e32 v154, v156
	v_permlane32_swap_b32_e32 v155, v157
	v_permlane32_swap_b32_e32 v158, v160
	v_permlane32_swap_b32_e32 v159, v161
	s_and_b64 vcc, exec, s[40:41]
	s_cbranch_vccz .Latt_nomask
	v_mov_b32_e32 v74, v246
	v_mov_b32_e32 v75, v246
	v_mov_b32_e32 v76, v246
	v_mov_b32_e32 v77, v246
	v_mov_b32_e32 v78, v246
	v_mov_b32_e32 v79, v246
	v_mov_b32_e32 v80, v246
	v_mov_b32_e32 v81, v246
	v_mov_b32_e32 v82, v246
	v_mov_b32_e32 v83, v246
	v_mov_b32_e32 v84, v246
	v_mov_b32_e32 v85, v246
	v_mov_b32_e32 v86, v246
	v_mov_b32_e32 v87, v246
	v_mov_b32_e32 v88, v246
	v_mov_b32_e32 v89, v246
	v_mov_b32_e32 v90, v246
	v_mov_b32_e32 v91, v246
	v_mov_b32_e32 v92, v246
	v_mov_b32_e32 v93, v246
	v_mov_b32_e32 v94, v246
	v_mov_b32_e32 v95, v246
	v_mov_b32_e32 v96, v246
	v_mov_b32_e32 v97, v246
; #define SBAR() __builtin_amdgcn_sched_barrier(0)
; #define SLOAD(i, t) do { const long rb_ = TROW(t); const char* vt_ = (const char*)Vh + rb_ * (LDK * 2); const char* kt_ = (const char*)Kh + rb_ * (LDK * 2); \
;     sr_[i].vs0 = *(const bf16x8*)(vt_ + lo0); sr_[i].vs1 = *(const bf16x8*)(vt_ + lo0 + 32 * LDK * 2); \
;     sr_[i].ks0 = *(const bf16x8*)(kt_ + lo0); sr_[i].ks1 = *(const bf16x8*)(kt_ + lo0 + 32 * LDK * 2); } while (0)
; #define SWRITE(bb, i) do { *(bf16x8*)((char*)V_lds + (bb) * SHM_V + vst0) = sr_[i].vs0;          \
;     *(bf16x8*)((char*)V_lds + (bb) * SHM_V + vst1) = sr_[i].vs1; int kc = sc * 2;               \
;     *(bf16x8*)((char*)K_lds + (bb) * SHM_K + KSWZ(sr, kc)) = sr_[i].ks0;                       \
;     *(bf16x8*)((char*)K_lds + (bb) * SHM_K + KSWZ(32 + sr, kc)) = sr_[i].ks1; } while (0)
; template <int D0> __device__ __forceinline__ void pv_one(f32x16& od, int vb, bf16x8 pa0, bf16x8 pa1, bf16x8 pa2, bf16x8 pa3) {
;   const s16x4 l0 = tr_read<v_rd_off(D0, 0, 0)>(vb), h0 = tr_read<v_rd_off(D0, 0, 1)>(vb), l1 = tr_read<v_rd_off(D0, 1, 0)>(vb), h1 = tr_read<v_rd_off(D0, 1, 1)>(vb);
;   const s16x4 l2 = tr_read<v_rd_off(D0, 2, 0)>(vb), h2 = tr_read<v_rd_off(D0, 2, 1)>(vb), l3 = tr_read<v_rd_off(D0, 3, 0)>(vb), h3 = tr_read<v_rd_off(D0, 3, 1)>(vb);
;   asm volatile("s_waitcnt lgkmcnt(0)" ::: "memory"); SBAR();
;     ...
;   od = __builtin_amdgcn_mfma_f32_32x32x16_bf16(pa0, PK(l0, h0), od, 0, 0, 0);
;   od = __builtin_amdgcn_mfma_f32_32x32x16_bf16(pa1, PK(l1, h1), od, 0, 0, 0);
;   od = __builtin_amdgcn_mfma_f32_32x32x16_bf16(pa2, PK(l2, h2), od, 0, 0, 0);
;   od = __builtin_amdgcn_mfma_f32_32x32x16_bf16(pa3, PK(l3, h3), od, 0, 0, 0);
;     ...
; }
; __device__ __forceinline__ void pv_d0(f32x16* o, int vb, bf16x8 pa0, bf16x8 pa1, bf16x8 pa2, bf16x8 pa3) {
;   pv_one<0>(o[0], vb, pa0, pa1, pa2, pa3); pv_one<1>(o[1], vb, pa0, pa1, pa2, pa3); pv_one<2>(o[2], vb, pa0, pa1, pa2, pa3); pv_one<3>(o[3], vb, pa0, pa1, pa2, pa3);
; template <bool META>
; __device__ __forceinline__ void attn_unit(const bf16_t* Q, bf16_t* Oo, const bf16_t* __restrict__ Kb, const bf16_t* __restrict__ Vb, int b, int kvh, int h, int qb, char* lds, const int tid, const float* qn, const float* RT) {
;     ...
;     if (j + 2 < NT) SLOAD(SE, j + 2);
;     SBAR();
;     pv_d0(o, vb0 + bc * (int)SHM_V, pa0, pa1, pa2, pa3); partialSM(pA0, pA1, m_reg, mnA, alA);
;     SWAIT(); SWRITE(bp, SO);
.Latt_nomask:
	v_add_u32_e32 v198, s9, v178
	ds_read_b64_tr_b16 v[212:213], v198 offset:0
	ds_read_b64_tr_b16 v[214:215], v198 offset:0x800
	ds_read_b64_tr_b16 v[216:217], v198 offset:0x1000
	ds_read_b64_tr_b16 v[218:219], v198 offset:0x1800
	ds_read_b64_tr_b16 v[220:221], v198 offset:0x2000
	ds_read_b64_tr_b16 v[222:223], v198 offset:0x2800
	ds_read_b64_tr_b16 v[224:225], v198 offset:0x3000
	ds_read_b64_tr_b16 v[226:227], v198 offset:0x3800
	s_andn2_b64 vcc, exec, s[0:1]
	s_cbranch_vccnz .LBB0_266
	s_add_u32 s0, s90, 64
	s_addc_u32 s1, s91, 0
	s_cmpk_lt_u32 s4, 0xfe
	s_cselect_b32 s1, s1, s44
	s_cselect_b32 s0, s0, s31
	s_lshl_b64 s[0:1], s[0:1], 9
	s_add_i32 s19, s8, s18
	s_add_u32 s16, s12, s0
	s_addc_u32 s17, s13, s1
	s_mov_b32 m0, s19
	s_nop 0
	global_load_lds_dwordx4 v187, s[16:17]
	s_add_i32 m0, s19, 0x380
	s_nop 0
	global_load_lds_dwordx4 v187, s[16:17] offset:128
	s_add_u32 s16, s14, s0
	s_addc_u32 s17, s15, s1
	s_add_i32 m0, s19, 0xc000
	s_nop 0
	global_load_lds_dwordx4 v188, s[16:17]
	s_add_u32 s16, s16, 0x4000
	s_addc_u32 s17, s17, 0
	s_add_i32 m0, s19, 0xc400
	s_nop 0
	global_load_lds_dwordx4 v188, s[16:17]
.LBB0_266:
	s_waitcnt lgkmcnt(6)
	s_nop 0
	v_mfma_f32_32x32x16_bf16 v[2:17], v[146:149], v[212:215], v[2:17]
	ds_read_b64_tr_b16 v[212:213], v198 offset:0x200
	ds_read_b64_tr_b16 v[214:215], v198 offset:0xa00
	s_waitcnt lgkmcnt(6)
	v_mfma_f32_32x32x16_bf16 v[2:17], v[150:153], v[216:219], v[2:17]
	ds_read_b64_tr_b16 v[216:217], v198 offset:0x1200
	ds_read_b64_tr_b16 v[218:219], v198 offset:0x1a00
	s_waitcnt lgkmcnt(6)
	v_mfma_f32_32x32x16_bf16 v[2:17], v[154:157], v[220:223], v[2:17]
	ds_read_b64_tr_b16 v[220:221], v198 offset:0x2200
	ds_read_b64_tr_b16 v[222:223], v198 offset:0x2a00
	s_waitcnt lgkmcnt(6)
	v_mfma_f32_32x32x16_bf16 v[2:17], v[158:161], v[224:227], v[2:17]
	ds_read_b64_tr_b16 v[224:225], v198 offset:0x3200
	ds_read_b64_tr_b16 v[226:227], v198 offset:0x3a00
	s_waitcnt lgkmcnt(6)
	v_mfma_f32_32x32x16_bf16 v[50:65], v[146:149], v[212:215], v[50:65]
	ds_read_b64_tr_b16 v[212:213], v198 offset:0x400
	ds_read_b64_tr_b16 v[214:215], v198 offset:0xc00
	s_waitcnt lgkmcnt(6)
	v_mfma_f32_32x32x16_bf16 v[50:65], v[150:153], v[216:219], v[50:65]
	ds_read_b64_tr_b16 v[216:217], v198 offset:0x1400
	ds_read_b64_tr_b16 v[218:219], v198 offset:0x1c00
	s_waitcnt lgkmcnt(6)
	v_mfma_f32_32x32x16_bf16 v[50:65], v[154:157], v[220:223], v[50:65]
	ds_read_b64_tr_b16 v[220:221], v198 offset:0x2400
	ds_read_b64_tr_b16 v[222:223], v198 offset:0x2c00
	s_waitcnt lgkmcnt(6)
	v_mfma_f32_32x32x16_bf16 v[50:65], v[158:161], v[224:227], v[50:65]
	ds_read_b64_tr_b16 v[224:225], v198 offset:0x3400
	ds_read_b64_tr_b16 v[226:227], v198 offset:0x3c00
	s_waitcnt lgkmcnt(6)
	v_mfma_f32_32x32x16_bf16 v[34:49], v[146:149], v[212:215], v[34:49]
	ds_read_b64_tr_b16 v[212:213], v198 offset:0x600
	ds_read_b64_tr_b16 v[214:215], v198 offset:0xe00
	s_waitcnt lgkmcnt(6)
	v_mfma_f32_32x32x16_bf16 v[34:49], v[150:153], v[216:219], v[34:49]
	ds_read_b64_tr_b16 v[216:217], v198 offset:0x1600
	ds_read_b64_tr_b16 v[218:219], v198 offset:0x1e00
	s_waitcnt lgkmcnt(6)
	v_mfma_f32_32x32x16_bf16 v[34:49], v[154:157], v[220:223], v[34:49]
	ds_read_b64_tr_b16 v[220:221], v198 offset:0x2600
	ds_read_b64_tr_b16 v[222:223], v198 offset:0x2e00
	s_waitcnt lgkmcnt(6)
	v_mfma_f32_32x32x16_bf16 v[34:49], v[158:161], v[224:227], v[34:49]
	ds_read_b64_tr_b16 v[224:225], v198 offset:0x3600
	ds_read_b64_tr_b16 v[226:227], v198 offset:0x3e00
	s_waitcnt lgkmcnt(6)
	v_mfma_f32_32x32x16_bf16 v[18:33], v[146:149], v[212:215], v[18:33]
	v_max_f32_e32 v230, v66, v67
	v_max3_f32 v230, v230, v68, v69
	v_max3_f32 v230, v230, v70, v71
	v_max3_f32 v230, v230, v72, v73
	v_max3_f32 v230, v230, v74, v75
	v_max3_f32 v230, v230, v76, v77
	v_max3_f32 v230, v230, v78, v79
	s_waitcnt lgkmcnt(4)
	v_mfma_f32_32x32x16_bf16 v[18:33], v[150:153], v[216:219], v[18:33]
	v_max3_f32 v230, v230, v80, v81
	v_max3_f32 v230, v230, v82, v83
	v_max3_f32 v230, v230, v84, v85
	v_max3_f32 v230, v230, v86, v87
	v_max3_f32 v230, v230, v88, v89
	v_max3_f32 v230, v230, v90, v91
	v_max3_f32 v230, v230, v92, v93
	v_max3_f32 v230, v230, v94, v95
	s_waitcnt lgkmcnt(2)
	v_mfma_f32_32x32x16_bf16 v[18:33], v[154:157], v[220:223], v[18:33]
	v_max3_f32 v230, v230, v96, v97
	v_mov_b32_e32 v231, v230
	s_nop 1
	v_permlane32_swap_b32_e32 v230, v231
	v_max_f32_e32 v230, v230, v231
	v_sub_f32_e32 v231, v230, v209
	v_cmp_ge_f32_e32 vcc, s25, v231
	v_max_f32_e32 v231, v209, v230
	s_waitcnt lgkmcnt(0)
	v_mfma_f32_32x32x16_bf16 v[18:33], v[158:161], v[224:227], v[18:33]
	v_sub_f32_e32 v230, v209, v231
	v_mul_f32_e32 v230, 0x3e0293ee, v230
	s_cmp_eq_u64 vcc, exec
	v_exp_f32_e32 v230, v230
	s_cselect_b64 s[40:41], -1, 0
	s_add_i32 s0, s8, 0
	v_cndmask_b32_e64 v230, v230, 1.0, s[40:41]
	v_cmp_gt_f32_e32 vcc, 1.0, v230
	s_cbranch_vccz .LBB0_270
	s_and_saveexec_b64 s[0:1], s[38:39]
	ds_write_b32 v190, v230 offset:128
	s_or_b64 exec, exec, s[0:1]
	s_waitcnt lgkmcnt(0)
	v_add_u32_e32 v236, v173, v181
	ds_read_b128 v[232:235], v236 offset:224
	ds_read_b128 v[130:133], v236 offset:192
	ds_read_b128 v[134:137], v236 offset:160
	ds_read_b128 v[138:141], v236 offset:128
	s_waitcnt lgkmcnt(3)
	v_pk_mul_f32 v[14:15], v[14:15], v[232:233]
	s_waitcnt lgkmcnt(2)
	v_pk_mul_f32 v[10:11], v[10:11], v[130:131]
	s_waitcnt lgkmcnt(1)
	v_pk_mul_f32 v[6:7], v[6:7], v[134:135]
	v_pk_mul_f32 v[16:17], v[16:17], v[234:235]
	v_pk_mul_f32 v[12:13], v[12:13], v[132:133]
	v_pk_mul_f32 v[8:9], v[8:9], v[136:137]
	s_waitcnt lgkmcnt(0)
	v_pk_mul_f32 v[4:5], v[4:5], v[140:141]
	v_pk_mul_f32 v[2:3], v[2:3], v[138:139]
	v_pk_mul_f32 v[62:63], v[62:63], v[232:233]
	v_pk_mul_f32 v[58:59], v[58:59], v[130:131]
	v_pk_mul_f32 v[54:55], v[54:55], v[134:135]
	v_pk_mul_f32 v[64:65], v[64:65], v[234:235]
	v_pk_mul_f32 v[60:61], v[60:61], v[132:133]
	v_pk_mul_f32 v[56:57], v[56:57], v[136:137]
	v_pk_mul_f32 v[52:53], v[52:53], v[140:141]
	v_pk_mul_f32 v[50:51], v[50:51], v[138:139]
	v_pk_mul_f32 v[46:47], v[46:47], v[232:233]
	v_pk_mul_f32 v[42:43], v[42:43], v[130:131]
	v_pk_mul_f32 v[38:39], v[38:39], v[134:135]
	v_pk_mul_f32 v[48:49], v[48:49], v[234:235]
	v_pk_mul_f32 v[44:45], v[44:45], v[132:133]
	v_pk_mul_f32 v[40:41], v[40:41], v[136:137]
	v_pk_mul_f32 v[36:37], v[36:37], v[140:141]
	v_pk_mul_f32 v[34:35], v[34:35], v[138:139]
	v_pk_mul_f32 v[30:31], v[30:31], v[232:233]
	v_pk_mul_f32 v[26:27], v[26:27], v[130:131]
	v_pk_mul_f32 v[22:23], v[22:23], v[134:135]
	v_pk_mul_f32 v[32:33], v[32:33], v[234:235]
	v_pk_mul_f32 v[28:29], v[28:29], v[132:133]
	v_pk_mul_f32 v[24:25], v[24:25], v[136:137]
	v_pk_mul_f32 v[20:21], v[20:21], v[140:141]
	v_pk_mul_f32 v[18:19], v[18:19], v[138:139]
